# v88 + metafuse: meta-token SSM item on WGs 0-7 reuses item c's B fragments/decay regs, u fragments prefetched (no 2nd prologue)
# baseline (speedup 1.0000x reference)
; __device__ __forceinline__ f32x2 pk_fma(f32x2 a, f32x2 b, f32x2 c) { return __builtin_elementwise_fma(a, b, c); }
; template <bool FINAL>
; __device__ __forceinline__ void ssm_item(const Args& a, LAS unsigned char* lds, int item, int wave, int lane) {
;     ...
;     for (int st = 0; st < nsteps; ++st) {
;         bf16x8 ufn = uf; u32x2 un0 = uu0, un1 = uu1;
;         if (st + 1 < nsteps) { ufn = *(const bf16x8*)(up + (size_t)(st + 1) * 8 * DM);
;             if (FINAL) { un0 = *(const u32x2*)(ue + (size_t)(st + 1) * 8 * DM); un1 = *(const u32x2*)(ue + (size_t)(st + 1) * 8 * DM + (size_t)SEQ * DM); } }
;         f32x16 X[4];
; #pragma unroll
;         for (int k = 0; k < 4; ++k) { f32x16 z;
; #pragma unroll
;             for (int e = 0; e < 16; ++e) z[e] = 0.f;
;             X[k] = __builtin_amdgcn_mfma_f32_32x32x16_bf16(uf, bbf[k], z, 0, 0, 0); }
; #pragma unroll
;         for (int t = 0; t < 8; ++t) {
;             const f32x2 x0r = (f32x2){X[0][2 * t], X[0][2 * t + 1]}, x0i = (f32x2){X[1][2 * t], X[1][2 * t + 1]}, x1r = (f32x2){X[2][2 * t], X[2][2 * t + 1]}, x1i = (f32x2){X[3][2 * t], X[3][2 * t + 1]};
;             const f32x2 n0r = pk_fma(a0x, s0r, pk_fma(na0y, s0i, x0r)), n0i = pk_fma(a0x, s0i, pk_fma(a0y, s0r, x0i));
;             const f32x2 n1r = pk_fma(a1x, s1r, pk_fma(na1y, s1i, x1r)), n1i = pk_fma(a1x, s1i, pk_fma(a1y, s1r, x1i));
;             s0r = n0r; s0i = n0i; s1r = n1r; s1i = n1i;
.LBB0_264:
	s_add_i32 s20, s20, s92
	s_add_i32 s19, s19, s96
	s_cmpk_gt_i32 s20, 0x107
	s_cbranch_scc1 .LBB0_274
	v_mov_b32_e32 v120, 0
	v_mov_b32_e32 v121, 0
	v_mov_b32_e32 v122, 0
	v_mov_b32_e32 v123, 0
	v_mov_b32_e32 v124, 0
	v_mov_b32_e32 v125, 0
	v_mov_b32_e32 v126, 0
	v_mov_b32_e32 v127, 0
	s_waitcnt vmcnt(4)
	v_mfma_f32_32x32x16_bf16 v[0:15], v[136:139], v[68:71], 0
	v_mfma_f32_32x32x16_bf16 v[16:31], v[136:139], v[72:75], 0
	v_mfma_f32_32x32x16_bf16 v[32:47], v[136:139], v[76:79], 0
	v_mfma_f32_32x32x16_bf16 v[48:63], v[136:139], v[64:67], 0
	s_nop 15
	v_pk_fma_f32 v[0:1], v[106:107], v[122:123], v[0:1]
	v_pk_fma_f32 v[16:17], v[98:99], v[120:121], v[16:17]
	v_pk_fma_f32 v[32:33], v[108:109], v[126:127], v[32:33]
	v_pk_fma_f32 v[48:49], v[96:97], v[124:125], v[48:49]
	v_pk_fma_f32 v[0:1], v[100:101], v[120:121], v[0:1]
	v_pk_fma_f32 v[16:17], v[100:101], v[122:123], v[16:17]
	v_pk_fma_f32 v[32:33], v[102:103], v[124:125], v[32:33]
	v_pk_fma_f32 v[48:49], v[102:103], v[126:127], v[48:49]
	v_pk_fma_f32 v[2:3], v[106:107], v[16:17], v[2:3]
	v_pk_fma_f32 v[18:19], v[98:99], v[0:1], v[18:19]
	v_pk_fma_f32 v[34:35], v[108:109], v[48:49], v[34:35]
	v_pk_fma_f32 v[50:51], v[96:97], v[32:33], v[50:51]
	v_pk_fma_f32 v[2:3], v[100:101], v[0:1], v[2:3]
	v_pk_fma_f32 v[18:19], v[100:101], v[16:17], v[18:19]
	v_pk_fma_f32 v[34:35], v[102:103], v[32:33], v[34:35]
	v_pk_fma_f32 v[50:51], v[102:103], v[48:49], v[50:51]
	v_pk_fma_f32 v[4:5], v[106:107], v[18:19], v[4:5]
	v_pk_fma_f32 v[20:21], v[98:99], v[2:3], v[20:21]
	v_pk_fma_f32 v[36:37], v[108:109], v[50:51], v[36:37]
	v_pk_fma_f32 v[52:53], v[96:97], v[34:35], v[52:53]
	v_pk_fma_f32 v[4:5], v[100:101], v[2:3], v[4:5]
	v_pk_fma_f32 v[20:21], v[100:101], v[18:19], v[20:21]
	v_pk_fma_f32 v[36:37], v[102:103], v[34:35], v[36:37]
	v_pk_fma_f32 v[52:53], v[102:103], v[50:51], v[52:53]
	v_pk_fma_f32 v[6:7], v[106:107], v[20:21], v[6:7]
	v_pk_fma_f32 v[22:23], v[98:99], v[4:5], v[22:23]
	v_pk_fma_f32 v[38:39], v[108:109], v[52:53], v[38:39]
	v_pk_fma_f32 v[54:55], v[96:97], v[36:37], v[54:55]
	v_pk_fma_f32 v[6:7], v[100:101], v[4:5], v[6:7]
	v_pk_fma_f32 v[22:23], v[100:101], v[20:21], v[22:23]
	v_pk_fma_f32 v[38:39], v[102:103], v[36:37], v[38:39]
	v_pk_fma_f32 v[54:55], v[102:103], v[52:53], v[54:55]
	v_pk_fma_f32 v[8:9], v[106:107], v[22:23], v[8:9]
	v_pk_fma_f32 v[24:25], v[98:99], v[6:7], v[24:25]
	v_pk_fma_f32 v[40:41], v[108:109], v[54:55], v[40:41]
	v_pk_fma_f32 v[56:57], v[96:97], v[38:39], v[56:57]
	v_pk_fma_f32 v[8:9], v[100:101], v[6:7], v[8:9]
	v_pk_fma_f32 v[24:25], v[100:101], v[22:23], v[24:25]
	v_pk_fma_f32 v[40:41], v[102:103], v[38:39], v[40:41]
	v_pk_fma_f32 v[56:57], v[102:103], v[54:55], v[56:57]
	v_pk_fma_f32 v[10:11], v[106:107], v[24:25], v[10:11]
	v_pk_fma_f32 v[26:27], v[98:99], v[8:9], v[26:27]
	v_pk_fma_f32 v[42:43], v[108:109], v[56:57], v[42:43]
	v_pk_fma_f32 v[58:59], v[96:97], v[40:41], v[58:59]
	v_pk_fma_f32 v[10:11], v[100:101], v[8:9], v[10:11]
	v_pk_fma_f32 v[26:27], v[100:101], v[24:25], v[26:27]
	v_pk_fma_f32 v[42:43], v[102:103], v[40:41], v[42:43]
	v_pk_fma_f32 v[58:59], v[102:103], v[56:57], v[58:59]
	v_pk_fma_f32 v[12:13], v[106:107], v[26:27], v[12:13]
	v_pk_fma_f32 v[28:29], v[98:99], v[10:11], v[28:29]
	v_pk_fma_f32 v[44:45], v[108:109], v[58:59], v[44:45]
	v_pk_fma_f32 v[60:61], v[96:97], v[42:43], v[60:61]
	v_pk_fma_f32 v[12:13], v[100:101], v[10:11], v[12:13]
	v_pk_fma_f32 v[28:29], v[100:101], v[26:27], v[28:29]
	v_pk_fma_f32 v[44:45], v[102:103], v[42:43], v[44:45]
	v_pk_fma_f32 v[60:61], v[102:103], v[58:59], v[60:61]
	v_pk_fma_f32 v[14:15], v[106:107], v[28:29], v[14:15]
	v_pk_fma_f32 v[30:31], v[98:99], v[12:13], v[30:31]
	v_pk_fma_f32 v[46:47], v[108:109], v[60:61], v[46:47]
	v_pk_fma_f32 v[62:63], v[96:97], v[44:45], v[62:63]
	v_pk_fma_f32 v[120:121], v[100:101], v[12:13], v[14:15]
	v_pk_fma_f32 v[122:123], v[100:101], v[28:29], v[30:31]
	v_pk_fma_f32 v[124:125], v[102:103], v[44:45], v[46:47]
; __device__ __forceinline__ f32x2 pk_fma(f32x2 a, f32x2 b, f32x2 c) { return __builtin_elementwise_fma(a, b, c); }
; template <bool FINAL>
; __device__ __forceinline__ void ssm_item(const Args& a, LAS unsigned char* lds, int item, int wave, int lane) {
;     ...
;     for (int st = 0; st < nsteps; ++st) {
;         bf16x8 ufn = uf; u32x2 un0 = uu0, un1 = uu1;
;         if (st + 1 < nsteps) { ufn = *(const bf16x8*)(up + (size_t)(st + 1) * 8 * DM);
;             if (FINAL) { un0 = *(const u32x2*)(ue + (size_t)(st + 1) * 8 * DM); un1 = *(const u32x2*)(ue + (size_t)(st + 1) * 8 * DM + (size_t)SEQ * DM); } }
;         f32x16 X[4];
; #pragma unroll
;         for (int k = 0; k < 4; ++k) { f32x16 z;
; #pragma unroll
;             for (int e = 0; e < 16; ++e) z[e] = 0.f;
;             X[k] = __builtin_amdgcn_mfma_f32_32x32x16_bf16(uf, bbf[k], z, 0, 0, 0); }
; #pragma unroll
;         for (int t = 0; t < 8; ++t) {
;             const f32x2 x0r = (f32x2){X[0][2 * t], X[0][2 * t + 1]}, x0i = (f32x2){X[1][2 * t], X[1][2 * t + 1]}, x1r = (f32x2){X[2][2 * t], X[2][2 * t + 1]}, x1i = (f32x2){X[3][2 * t], X[3][2 * t + 1]};
;             const f32x2 n0r = pk_fma(a0x, s0r, pk_fma(na0y, s0i, x0r)), n0i = pk_fma(a0x, s0i, pk_fma(a0y, s0r, x0i));
;             const f32x2 n1r = pk_fma(a1x, s1r, pk_fma(na1y, s1i, x1r)), n1i = pk_fma(a1x, s1i, pk_fma(a1y, s1r, x1i));
;             s0r = n0r; s0i = n0i; s1r = n1r; s1i = n1i;
	v_pk_fma_f32 v[126:127], v[102:103], v[60:61], v[62:63]
	v_mfma_f32_32x32x16_bf16 v[0:15], v[140:143], v[68:71], 0
	v_mfma_f32_32x32x16_bf16 v[16:31], v[140:143], v[72:75], 0
	v_mfma_f32_32x32x16_bf16 v[32:47], v[140:143], v[76:79], 0
	v_mfma_f32_32x32x16_bf16 v[48:63], v[140:143], v[64:67], 0
	s_nop 15
	v_pk_fma_f32 v[0:1], v[106:107], v[122:123], v[0:1]
	v_pk_fma_f32 v[16:17], v[98:99], v[120:121], v[16:17]
	v_pk_fma_f32 v[32:33], v[108:109], v[126:127], v[32:33]
	v_pk_fma_f32 v[48:49], v[96:97], v[124:125], v[48:49]
	v_pk_fma_f32 v[0:1], v[100:101], v[120:121], v[0:1]
	v_pk_fma_f32 v[16:17], v[100:101], v[122:123], v[16:17]
	v_pk_fma_f32 v[32:33], v[102:103], v[124:125], v[32:33]
	v_pk_fma_f32 v[48:49], v[102:103], v[126:127], v[48:49]
	v_pk_fma_f32 v[2:3], v[106:107], v[16:17], v[2:3]
	v_pk_fma_f32 v[18:19], v[98:99], v[0:1], v[18:19]
	v_pk_fma_f32 v[34:35], v[108:109], v[48:49], v[34:35]
	v_pk_fma_f32 v[50:51], v[96:97], v[32:33], v[50:51]
	v_pk_fma_f32 v[2:3], v[100:101], v[0:1], v[2:3]
	v_pk_fma_f32 v[18:19], v[100:101], v[16:17], v[18:19]
	v_pk_fma_f32 v[34:35], v[102:103], v[32:33], v[34:35]
	v_pk_fma_f32 v[50:51], v[102:103], v[48:49], v[50:51]
	v_pk_fma_f32 v[4:5], v[106:107], v[18:19], v[4:5]
	v_pk_fma_f32 v[20:21], v[98:99], v[2:3], v[20:21]
	v_pk_fma_f32 v[36:37], v[108:109], v[50:51], v[36:37]
	v_pk_fma_f32 v[52:53], v[96:97], v[34:35], v[52:53]
	v_pk_fma_f32 v[4:5], v[100:101], v[2:3], v[4:5]
	v_pk_fma_f32 v[20:21], v[100:101], v[18:19], v[20:21]
	v_pk_fma_f32 v[36:37], v[102:103], v[34:35], v[36:37]
	v_pk_fma_f32 v[52:53], v[102:103], v[50:51], v[52:53]
	v_pk_fma_f32 v[6:7], v[106:107], v[20:21], v[6:7]
	v_pk_fma_f32 v[22:23], v[98:99], v[4:5], v[22:23]
	v_pk_fma_f32 v[38:39], v[108:109], v[52:53], v[38:39]
	v_pk_fma_f32 v[54:55], v[96:97], v[36:37], v[54:55]
	v_pk_fma_f32 v[6:7], v[100:101], v[4:5], v[6:7]
	v_pk_fma_f32 v[22:23], v[100:101], v[20:21], v[22:23]
	v_pk_fma_f32 v[38:39], v[102:103], v[36:37], v[38:39]
	v_pk_fma_f32 v[54:55], v[102:103], v[52:53], v[54:55]
	v_pk_fma_f32 v[8:9], v[106:107], v[22:23], v[8:9]
	v_pk_fma_f32 v[24:25], v[98:99], v[6:7], v[24:25]
	v_pk_fma_f32 v[40:41], v[108:109], v[54:55], v[40:41]
	v_pk_fma_f32 v[56:57], v[96:97], v[38:39], v[56:57]
	v_pk_fma_f32 v[8:9], v[100:101], v[6:7], v[8:9]
	v_pk_fma_f32 v[24:25], v[100:101], v[22:23], v[24:25]
	v_pk_fma_f32 v[40:41], v[102:103], v[38:39], v[40:41]
	v_pk_fma_f32 v[56:57], v[102:103], v[54:55], v[56:57]
	v_pk_fma_f32 v[10:11], v[106:107], v[24:25], v[10:11]
	v_pk_fma_f32 v[26:27], v[98:99], v[8:9], v[26:27]
	v_pk_fma_f32 v[42:43], v[108:109], v[56:57], v[42:43]
	v_pk_fma_f32 v[58:59], v[96:97], v[40:41], v[58:59]
	v_pk_fma_f32 v[10:11], v[100:101], v[8:9], v[10:11]
	v_pk_fma_f32 v[26:27], v[100:101], v[24:25], v[26:27]
	v_pk_fma_f32 v[42:43], v[102:103], v[40:41], v[42:43]
	v_pk_fma_f32 v[58:59], v[102:103], v[56:57], v[58:59]
	v_pk_fma_f32 v[12:13], v[106:107], v[26:27], v[12:13]
	v_pk_fma_f32 v[28:29], v[98:99], v[10:11], v[28:29]
	v_pk_fma_f32 v[44:45], v[108:109], v[58:59], v[44:45]
	v_pk_fma_f32 v[60:61], v[96:97], v[42:43], v[60:61]
	v_pk_fma_f32 v[12:13], v[100:101], v[10:11], v[12:13]
	v_pk_fma_f32 v[28:29], v[100:101], v[26:27], v[28:29]
	v_pk_fma_f32 v[44:45], v[102:103], v[42:43], v[44:45]
	v_pk_fma_f32 v[60:61], v[102:103], v[58:59], v[60:61]
	v_pk_fma_f32 v[14:15], v[106:107], v[28:29], v[14:15]
	v_pk_fma_f32 v[30:31], v[98:99], v[12:13], v[30:31]
	v_pk_fma_f32 v[46:47], v[108:109], v[60:61], v[46:47]
	v_pk_fma_f32 v[62:63], v[96:97], v[44:45], v[62:63]
	v_pk_fma_f32 v[120:121], v[100:101], v[12:13], v[14:15]
	v_pk_fma_f32 v[122:123], v[100:101], v[28:29], v[30:31]
	v_pk_fma_f32 v[124:125], v[102:103], v[44:45], v[46:47]
	v_pk_fma_f32 v[126:127], v[102:103], v[60:61], v[62:63]
	v_mov_b64_e32 v[0:1], v[120:121]
	v_mov_b64_e32 v[4:5], v[122:123]
	v_mov_b64_e32 v[2:3], v[124:125]
	v_mov_b64_e32 v[6:7], v[126:127]
	s_branch .LBB0_272

; #define LAS __attribute__((address_space(3)))
; template <bool FINAL>
; __device__ __forceinline__ void ssm_item(const Args& a, LAS unsigned char* lds, int item, int wave, int lane) {
;     ...
;     const int bsel = (j >> 2) & 1, csel = j & 1, tt = ((j & 3) >> 1) + 2 * (j >> 3);
;     const size_t urow0 = meta ? (size_t)META_ROW + tt : (size_t)(b0 + bsel) * SEQ + (size_t)(c0 + csel) * CHUNK + tt;
;     const bf16* up = U + urow0 * DM + g * 16 + 8 * hi;
;     LAS unsigned char* sl = lds + wave * (32 * SP);
;     const int nsteps = meta ? 2 : CHUNK / 8;
;     const size_t erow = (size_t)b0 * SEQ + (size_t)(c0 + ((lane & 15) >> 3)) * CHUNK + (lane & 7);
;     const bf16* ue = U + erow * DM + g * 16 + 4 * (lane >> 4);
;     bf16* ze = Z + erow * DM + g * 16 + 4 * (lane >> 4);
;     bf16x8 uf = *(const bf16x8*)up;
;     u32x2 uu0 = (u32x2){0u, 0u}, uu1 = (u32x2){0u, 0u};
;     if (FINAL) { uu0 = *(const u32x2*)ue; uu1 = *(const u32x2*)(ue + (size_t)SEQ * DM); }
.LBB0_267:
	v_lshlrev_b32_e32 v0, 11, v0
	v_mov_b32_e32 v1, v85
	v_lshl_add_u64 v[2:3], s[52:53], 0, v[0:1]
	s_lshl_b32 s24, s10, 5
	s_mov_b32 s25, s11
	v_lshl_add_u64 v[2:3], v[2:3], 0, s[24:25]
	v_lshl_add_u64 v[2:3], v[2:3], 0, v[90:91]
	global_load_dwordx4 v[80:83], v[2:3], off
	s_lshl_b32 s17, s19, 4
	s_and_b32 s17, s17, 0x380
	s_add_i32 s17, s18, s17
	s_lshl_b32 s24, s17, 1
	s_waitcnt vmcnt(2)
	v_xor_b32_e32 v106, 0x80000000, v99
	s_waitcnt vmcnt(1)
	v_xor_b32_e32 v108, 0x80000000, v97
	v_lshl_add_u64 v[0:1], v[0:1], 0, s[24:25]
	v_mov_b32_e32 v48, 0
	v_mov_b32_e32 v100, v98
	v_mov_b32_e32 v101, v98
	v_mov_b32_e32 v98, v99
	v_mov_b32_e32 v107, v106
	v_mov_b32_e32 v102, v96
	v_mov_b32_e32 v103, v96
	v_mov_b32_e32 v96, v97
	v_mov_b32_e32 v109, v108
	s_add_i32 s16, s16, 1
	v_lshl_add_u64 v[110:111], v[88:89], 0, v[0:1]
	v_mov_b32_e32 v49, v48
	v_mov_b32_e32 v50, v48
	v_mov_b32_e32 v51, v48
	v_mov_b32_e32 v112, v48
	v_mov_b32_e32 v113, v48
	v_mov_b32_e32 v114, v48
	v_mov_b32_e32 v115, v48
	s_cmp_gt_u32 s20, 7
	s_cbranch_scc1 .Lssm1_nopre
	v_lshlrev_b32_e32 v144, 11, v118
	v_mov_b32_e32 v145, 0
	s_lshl_b32 s26, s10, 5
	s_mov_b32 s27, 0
	v_lshl_add_u64 v[144:145], s[52:53], 0, v[144:145]
	v_lshl_add_u64 v[144:145], v[144:145], 0, s[26:27]
	v_lshl_add_u64 v[144:145], v[144:145], 0, v[90:91]
	global_load_dwordx4 v[136:139], v[144:145], off
	v_lshl_add_u64 v[144:145], v[144:145], 0, s[12:13]
	global_load_dwordx4 v[140:143], v[144:145], off
.Lssm1_nopre:
	global_load_dwordx4 v[132:135], v[110:111], off
	v_lshl_add_u64 v[110:111], v[110:111], 0, s[12:13]
	s_add_i32 s29, s16, 1
	s_lshr_b32 s29, s29, 1
	v_mov_b32_e32 v120, 0
	v_mov_b32_e32 v121, 0
	v_mov_b32_e32 v122, 0
	v_mov_b32_e32 v123, 0
	v_mov_b32_e32 v124, 0
	v_mov_b32_e32 v125, 0
	v_mov_b32_e32 v126, 0
	v_mov_b32_e32 v127, 0
